# v71: v68 + mixers phase: workgroups running the latent-query attention items (C-lat prio 3, B-lat prio 2) get issue priority over the co-resident workgroup; 0 elsewhere
# baseline (speedup 1.0000x reference)
.LBB0_471:
	s_cmpk_gt_i32 s4, 0x1df
	s_mov_b64 s[0:1], -1
	s_cbranch_scc1 .LBB0_470
	s_cmpk_lt_i32 s4, 96
	s_cbranch_scc0 .Lmix_prio_lo
	s_cmpk_lt_i32 s4, 64
	s_cbranch_scc0 .Lmix_prio_mid
	s_setprio 3
	s_branch .Lmix_prio_set
.Lmix_prio_mid:
	s_setprio 2
	s_branch .Lmix_prio_set
.Lmix_prio_lo:
	s_setprio 0
.Lmix_prio_set:
	s_cmpk_gt_i32 s4, 0x11f
	s_cbranch_scc0 .LBB0_478
	s_and_b32 s5, s4, 3
	s_cmpk_gt_u32 s4, 0x17f
	s_cbranch_scc0 .LBB0_492
	s_add_i32 s0, s4, 0xfffffe80
	s_lshr_b32 s1, s0, 2
	s_cmp_lt_u32 s0, 64
	v_mov_b32_e32 v0, v160
	s_cselect_b32 s0, s96, s95
	s_add_i32 s1, s1, s0
	v_ashrrev_i32_e32 v2, 1, v0
	v_and_b32_e32 v2, 0xffffffe0, v2
	v_and_b32_e32 v61, 31, v0
	v_lshl_add_u32 v2, s1, 7, v2
	v_or_b32_e32 v54, v2, v61
	v_bfe_u32 v60, v0, 5, 1
	s_lshl_b32 s6, s5, 6
	v_cmp_gt_i32_e32 vcc, s58, v54
	v_mov_b32_e32 v3, 0x400
	v_mov_b32_e32 v4, 0x100
	s_lshl_b32 s8, 2, s5
	v_lshl_or_b32 v33, v60, 3, s6
	v_cndmask_b32_e32 v72, v3, v4, vcc
	v_cndmask_b32_e32 v3, v205, v206, vcc
	s_lshr_b32 s7, s8, 1
	v_lshl_or_b32 v0, v33, 1, v207
	v_mov_b32_e32 v6, v1
	v_mov_b32_e32 v7, v1
	v_and_b32_e32 v73, v3, v2
	v_lshl_add_u64 v[16:17], s[36:37], 0, v[0:1]
	v_subrev_u32_e32 v32, s7, v54
	v_mov_b32_e32 v0, v1
	v_mov_b32_e32 v2, v1
	v_mov_b32_e32 v3, v1
	v_mov_b32_e32 v4, v1
	v_mov_b32_e32 v5, v1
	v_mov_b64_e32 v[14:15], v[6:7]
	s_mov_b32 s2, 0
	v_sub_u32_e32 v74, 0, v73
	v_sub_u32_e32 v36, v32, v73
	v_mov_b64_e32 v[12:13], v[4:5]
	v_mov_b64_e32 v[10:11], v[2:3]
	v_mov_b64_e32 v[8:9], v[0:1]
	s_mov_b64 s[100:101], exec
	v_and_b32_e32 v142, 7, v160
	v_bfe_u32 v143, v160, 3, 3
	v_sub_u32_e32 v144, v54, v61
	v_add_u32_e32 v144, v144, v143
	v_add_u32_e32 v144, -8, v144
	v_sub_u32_e32 v145, v144, v73
	v_lshlrev_b32_e32 v146, 12, v144
	v_lshl_add_u32 v146, v142, 4, v146
	s_lshl_b32 s98, s5, 7
	s_addk_i32 s98, 0xe00
	s_mov_b32 s99, 0xffff0000
	v_add_u32_e32 v146, s98, v146
	v_mov_b32_e32 v118, 0
	v_mov_b32_e32 v119, 0
	v_mov_b32_e32 v120, 0
	v_mov_b32_e32 v121, 0
	v_mov_b32_e32 v122, 0
	v_mov_b32_e32 v123, 0
	v_mov_b32_e32 v124, 0
	v_mov_b32_e32 v125, 0
	v_mov_b32_e32 v126, 0
	v_mov_b32_e32 v127, 0
	v_mov_b32_e32 v128, 0
	v_mov_b32_e32 v129, 0
	v_mov_b32_e32 v130, 0
	v_mov_b32_e32 v131, 0
	v_mov_b32_e32 v132, 0
	v_mov_b32_e32 v133, 0
	v_mov_b32_e32 v134, 0
	v_mov_b32_e32 v135, 0
	v_mov_b32_e32 v136, 0
	v_mov_b32_e32 v137, 0
	v_mov_b32_e32 v138, 0
	v_mov_b32_e32 v139, 0
	v_mov_b32_e32 v140, 0
	v_mov_b32_e32 v141, 0
	v_cmp_lt_u32_e32 vcc, v145, v72
	s_and_b64 exec, s[100:101], vcc
	global_load_dwordx4 v[118:121], v146, s[36:37]
	s_mov_b64 exec, s[100:101]
	v_add_u32_e32 v147, 8, v145
	v_add_u32_e32 v148, 0x8000, v146
	v_cmp_lt_u32_e32 vcc, v147, v72
	s_and_b64 exec, s[100:101], vcc
	global_load_dwordx4 v[122:125], v148, s[36:37]
	s_mov_b64 exec, s[100:101]
	v_add_u32_e32 v147, 16, v145
	v_add_u32_e32 v148, 0x10000, v146
	v_cmp_lt_u32_e32 vcc, v147, v72
	s_and_b64 exec, s[100:101], vcc
	global_load_dwordx4 v[126:129], v148, s[36:37]
	s_mov_b64 exec, s[100:101]
	v_add_u32_e32 v147, 24, v145
	v_add_u32_e32 v148, 0x18000, v146
	v_cmp_lt_u32_e32 vcc, v147, v72
	s_and_b64 exec, s[100:101], vcc
	global_load_dwordx4 v[130:133], v148, s[36:37]
	s_mov_b64 exec, s[100:101]
	v_add_u32_e32 v147, 32, v145
	v_add_u32_e32 v148, 0x20000, v146
	v_cmp_lt_u32_e32 vcc, v147, v72
	s_and_b64 exec, s[100:101], vcc
	global_load_dwordx4 v[134:137], v148, s[36:37]
	s_mov_b64 exec, s[100:101]
	v_add_u32_e32 v147, 40, v145
	v_add_u32_e32 v148, 0x28000, v146
	v_cmp_lt_u32_e32 vcc, v147, v72
	s_and_b64 exec, s[100:101], vcc
	global_load_dwordx4 v[138:141], v148, s[36:37]
	s_mov_b64 exec, s[100:101]
	v_lshrrev_b32_e32 v147, 6, v160
	v_mul_u32_u24_e32 v147, 0x1b00, v147
	v_mul_u32_u24_e32 v148, 0x90, v143
	v_add_u32_e32 v148, v148, v147
	v_lshl_add_u32 v148, v142, 4, v148
	v_add_u32_e32 v149, 8, v61
	v_subrev_u32_e32 v149, s7, v149
	v_mul_u32_u24_e32 v149, 0x90, v149
	v_add_u32_e32 v149, v149, v147
	v_lshl_add_u32 v158, v60, 4, v149
	s_waitcnt vmcnt(5)
	ds_write_b128 v148, v[118:121]
	s_waitcnt vmcnt(4)
	ds_write_b128 v148, v[122:125] offset:1152
	s_waitcnt vmcnt(3)
	ds_write_b128 v148, v[126:129] offset:2304
	s_waitcnt vmcnt(2)
	ds_write_b128 v148, v[130:133] offset:3456
	s_waitcnt vmcnt(1)
	ds_write_b128 v148, v[134:137] offset:4608
	s_waitcnt vmcnt(0)
	ds_write_b128 v148, v[138:141] offset:5760
	s_mov_b32 s98, 0
	v_mov_b32_e32 v159, v158

.LBB0_574:
	s_setprio 0
	s_getreg_b32 s2, hwreg(HW_REG_XCC_ID, 0, 4)
	s_waitcnt vmcnt(0)
	s_barrier
	s_and_saveexec_b64 s[0:1], s[14:15]
	v_readlane_b32 s34, v254, 58
	v_readlane_b32 s35, v254, 59
	s_cbranch_execz .LBB0_626
	v_readlane_b32 s98, v255, 63
	s_nop 0
	s_cmp_lg_u32 s98, 0
	s_cbranch_scc1 .Lhb_full_mix
	s_cmp_lg_u32 s33, 64
	s_cbranch_scc1 .Lhb_full_mix
	v_readlane_b32 s98, v255, 56
	v_readlane_b32 s100, v253, 1
	v_readlane_b32 s101, v253, 2
	v_readlane_b32 s99, v253, 0
	v_readlane_b32 vcc_lo, v254, 28
	s_add_i32 s98, s98, 1
	v_writelane_b32 v255, s98, 56
	s_lshl_b32 s99, s99, 14
	s_sub_u32 s100, s100, s99
	s_subb_u32 s101, s101, 0
	s_add_u32 s100, s100, 0xb000
	s_addc_u32 s101, s101, 0
	s_getreg_b32 s99, hwreg(HW_REG_XCC_ID, 0, 4)
	s_and_b32 s99, s99, 15
	s_lshl_b32 s99, s99, 8
	s_lshl_b32 vcc_hi, vcc_lo, 2
	s_add_i32 vcc_hi, vcc_hi, s99
	v_mov_b32_e32 v4, vcc_hi
	v_mov_b32_e32 v5, s98
	global_store_dword v4, v5, s[100:101]
	s_cmp_eq_u32 vcc_lo, 0
	s_cbranch_scc1 .Lhb_lead_mix
	s_lshr_b32 s99, s99, 2
	v_mov_b32_e32 v4, s99
	s_mov_b32 s99, 0
